# GEMM K-loops: LDS fragment reads reordered to first consumer (B0,A0..A3,B1..) with counted lgkmcnt so first MFMA waits for 2 reads not 5
# baseline (speedup 1.0000x reference)
; template <bool DEEP, class Epi>
; __device__ __forceinline__ void gemm_phase(const bf16_t* __restrict__ A, int lda, const bf16_t* __restrict__ Wt,
;                                            int K, int ntn, bool lat_only, const Epi& epi, char* smem) {
;     ...
;     for (int kt = 0; kt < nk; ++kt) {
;       __syncthreads();
;       GEMM_STORE(ra0, ra1, ra2, ra3, rb0, rb1, rb2, rb3, 0)
;       __syncthreads();
;       {
;         bf16x8 af0[4], bf0[4], af1[4], bf1[4];
;         __builtin_amdgcn_s_setprio(1);
; #pragma unroll
;         for (int i = 0; i < 4; ++i) af0[i] = *(const bf16x8*)(sA + (wm * 64 + i * 16 + l15) * LSTR + quad * 8);
; #pragma unroll
;         for (int j = 0; j < 4; ++j) bf0[j] = *(const bf16x8*)(sB + (wn * 64 + j * 16 + l15) * LSTR + quad * 8);
; #pragma unroll
;         for (int i = 0; i < 4; ++i) af1[i] = *(const bf16x8*)(sA + (wm * 64 + i * 16 + l15) * LSTR + 32 + quad * 8);
; #pragma unroll
;         for (int j = 0; j < 4; ++j) bf1[j] = *(const bf16x8*)(sB + (wn * 64 + j * 16 + l15) * LSTR + 32 + quad * 8);
;         __builtin_amdgcn_sched_barrier(0);
;         if (kt + 1 < nk) GEMM_LOAD(ra0, ra1, ra2, ra3, rb0, rb1, rb2, rb3, (kt + 1) * 64)
;         __builtin_amdgcn_sched_barrier(0);
; #pragma unroll
;         for (int i = 0; i < 4; ++i)
; #pragma unroll
;           for (int j = 0; j < 4; ++j) acc[i][j] = __builtin_amdgcn_mfma_f32_16x16x32_bf16(bf0[j], af0[i], acc[i][j], 0, 0, 0);
; #pragma unroll
;         for (int i = 0; i < 4; ++i)
; #pragma unroll
;           for (int j = 0; j < 4; ++j) acc[i][j] = __builtin_amdgcn_mfma_f32_16x16x32_bf16(bf1[j], af1[i], acc[i][j], 0, 0, 0);
;         __builtin_amdgcn_s_setprio(0);
.LBB0_139:
	s_waitcnt lgkmcnt(14)
	v_mfma_f32_16x16x32_bf16 v[60:63], v[136:139], v[156:159], v[60:63]
	s_waitcnt lgkmcnt(13)
	v_mfma_f32_16x16x32_bf16 v[56:59], v[140:143], v[156:159], v[56:59]
	s_waitcnt lgkmcnt(12)
	v_mfma_f32_16x16x32_bf16 v[52:55], v[144:147], v[156:159], v[52:55]
	s_waitcnt lgkmcnt(11)
	v_mfma_f32_16x16x32_bf16 v[48:51], v[148:151], v[156:159], v[48:51]
	s_waitcnt lgkmcnt(10)
	v_mfma_f32_16x16x32_bf16 v[44:47], v[136:139], v[152:155], v[44:47]
	v_mfma_f32_16x16x32_bf16 v[40:43], v[140:143], v[152:155], v[40:43]
	v_mfma_f32_16x16x32_bf16 v[36:39], v[144:147], v[152:155], v[36:39]
	v_mfma_f32_16x16x32_bf16 v[32:35], v[148:151], v[152:155], v[32:35]
	s_waitcnt lgkmcnt(9)
	v_mfma_f32_16x16x32_bf16 v[28:31], v[136:139], v[132:135], v[28:31]
	v_mfma_f32_16x16x32_bf16 v[24:27], v[140:143], v[132:135], v[24:27]
	v_mfma_f32_16x16x32_bf16 v[20:23], v[144:147], v[132:135], v[20:23]
	v_mfma_f32_16x16x32_bf16 v[16:19], v[148:151], v[132:135], v[16:19]
	s_waitcnt lgkmcnt(8)
	v_mfma_f32_16x16x32_bf16 v[12:15], v[136:139], v[124:127], v[12:15]
	v_mfma_f32_16x16x32_bf16 v[8:11], v[140:143], v[124:127], v[8:11]
	v_mfma_f32_16x16x32_bf16 v[4:7], v[144:147], v[124:127], v[4:7]
	v_mfma_f32_16x16x32_bf16 v[0:3], v[148:151], v[124:127], v[0:3]
	s_waitcnt lgkmcnt(6)
	v_mfma_f32_16x16x32_bf16 v[60:63], v[104:107], v[128:131], v[60:63]
	s_waitcnt lgkmcnt(5)
	v_mfma_f32_16x16x32_bf16 v[56:59], v[108:111], v[128:131], v[56:59]
	s_waitcnt lgkmcnt(4)
	v_mfma_f32_16x16x32_bf16 v[52:55], v[112:115], v[128:131], v[52:55]
	s_waitcnt lgkmcnt(3)
	v_mfma_f32_16x16x32_bf16 v[48:51], v[116:119], v[128:131], v[48:51]
	s_waitcnt lgkmcnt(2)
	v_mfma_f32_16x16x32_bf16 v[44:47], v[104:107], v[120:123], v[44:47]
	v_mfma_f32_16x16x32_bf16 v[40:43], v[108:111], v[120:123], v[40:43]
	v_mfma_f32_16x16x32_bf16 v[36:39], v[112:115], v[120:123], v[36:39]
	v_mfma_f32_16x16x32_bf16 v[32:35], v[116:119], v[120:123], v[32:35]
	s_waitcnt lgkmcnt(1)
	v_mfma_f32_16x16x32_bf16 v[28:31], v[104:107], v[100:103], v[28:31]
	v_mfma_f32_16x16x32_bf16 v[24:27], v[108:111], v[100:103], v[24:27]
	v_mfma_f32_16x16x32_bf16 v[20:23], v[112:115], v[100:103], v[20:23]
	v_mfma_f32_16x16x32_bf16 v[16:19], v[116:119], v[100:103], v[16:19]
	s_waitcnt lgkmcnt(0)
	v_mfma_f32_16x16x32_bf16 v[12:15], v[104:107], v[96:99], v[12:15]
	v_mfma_f32_16x16x32_bf16 v[8:11], v[108:111], v[96:99], v[8:11]
	v_mfma_f32_16x16x32_bf16 v[4:7], v[112:115], v[96:99], v[4:7]
	v_mfma_f32_16x16x32_bf16 v[0:3], v[116:119], v[96:99], v[0:3]
	s_setprio 0
	s_add_u32 s0, s0, 0x80
	s_addc_u32 s1, s1, 0
	s_cmpk_eq_i32 s0, 0x800
	s_cbranch_scc1 .LBB0_142
.LBB0_140:
	s_barrier
	s_waitcnt vmcnt(7)
	ds_write_b128 v165, v[64:67]
	s_waitcnt vmcnt(6)
	ds_write_b128 v165, v[68:71] offset:5120
	s_waitcnt vmcnt(5)
	ds_write_b128 v165, v[72:75] offset:10240
	s_waitcnt vmcnt(4)
	ds_write_b128 v165, v[76:79] offset:15360
	s_waitcnt vmcnt(3)
	ds_write_b128 v165, v[80:83] offset:20480
	s_waitcnt vmcnt(2)
	ds_write_b128 v165, v[84:87] offset:25600
	s_waitcnt vmcnt(1)
	ds_write_b128 v165, v[88:91] offset:30720
	s_waitcnt vmcnt(0)
	ds_write_b128 v165, v[92:95] offset:35840
	s_waitcnt lgkmcnt(0)
	s_barrier
	s_setprio 1
	v_add_u32_e32 v96, v173, v175
	ds_read_b128 v[156:159], v96
	ds_read_b128 v[136:139], v181 offset:20480
	ds_read_b128 v[140:143], v181 offset:23040
	ds_read_b128 v[144:147], v181 offset:25600
	ds_read_b128 v[148:151], v181 offset:28160
	ds_read_b128 v[152:155], v96 offset:2560
	ds_read_b128 v[132:135], v96 offset:5120
	ds_read_b128 v[124:127], v96 offset:7680
	ds_read_b128 v[128:131], v183 offset:64
	ds_read_b128 v[104:107], v185 offset:20544
	ds_read_b128 v[108:111], v185 offset:23104
	ds_read_b128 v[112:115], v185 offset:25664
	ds_read_b128 v[116:119], v185 offset:28224
	ds_read_b128 v[120:123], v183 offset:2624
	ds_read_b128 v[100:103], v183 offset:5184
	ds_read_b128 v[96:99], v183 offset:7744
	s_cmpk_eq_i32 s0, 0x780
	s_cbranch_scc1 .LBB0_139
	v_lshl_add_u64 v[72:73], v[238:239], 0, s[0:1]
	v_add_co_u32_e32 v64, vcc, 0x1d00000, v72
	v_lshl_add_u64 v[88:89], v[240:241], 0, s[0:1]
	s_nop 0
	v_addc_co_u32_e32 v65, vcc, 0, v73, vcc
	v_add_co_u32_e32 v68, vcc, 0x1d10000, v72
	s_nop 1
	v_addc_co_u32_e32 v69, vcc, 0, v73, vcc
	v_add_co_u32_e32 v74, vcc, 0x1d20000, v72
	global_load_dwordx4 v[64:67], v[64:65], off offset:128
	s_nop 0
	global_load_dwordx4 v[68:71], v[68:69], off offset:128
	v_addc_co_u32_e32 v75, vcc, 0, v73, vcc
	v_add_co_u32_e32 v76, vcc, 0x1d30000, v72
	s_nop 1
	v_addc_co_u32_e32 v77, vcc, 0, v73, vcc
	v_add_co_u32_e32 v84, vcc, 0x10000, v88
	global_load_dwordx4 v[72:75], v[74:75], off offset:128
	s_nop 0
	global_load_dwordx4 v[76:79], v[76:77], off offset:128
	v_addc_co_u32_e32 v85, vcc, 0, v89, vcc
	v_add_co_u32_e32 v90, vcc, 0x20000, v88
	global_load_dwordx4 v[80:83], v[88:89], off offset:128
	s_nop 0
	global_load_dwordx4 v[84:87], v[84:85], off offset:128
	v_addc_co_u32_e32 v91, vcc, 0, v89, vcc
	v_add_co_u32_e32 v92, vcc, 0x30000, v88
	s_nop 1
	v_addc_co_u32_e32 v93, vcc, 0, v89, vcc
	global_load_dwordx4 v[88:91], v[90:91], off offset:128
	s_nop 0
	global_load_dwordx4 v[92:95], v[92:93], off offset:128
	s_branch .LBB0_139

; template <bool DEEP, class Epi>
; __device__ __forceinline__ void gemm_phase(const bf16_t* __restrict__ A, int lda, const bf16_t* __restrict__ Wt,
;                                            int K, int ntn, bool lat_only, const Epi& epi, char* smem) {
;     ...
;     for (int kt = 0; kt < nk; ++kt) {
;       __syncthreads();
;       GEMM_STORE(ra0, ra1, ra2, ra3, rb0, rb1, rb2, rb3, 0)
;       __syncthreads();
;       {
;         bf16x8 af0[4], bf0[4], af1[4], bf1[4];
;         __builtin_amdgcn_s_setprio(1);
; #pragma unroll
;         for (int i = 0; i < 4; ++i) af0[i] = *(const bf16x8*)(sA + (wm * 64 + i * 16 + l15) * LSTR + quad * 8);
; #pragma unroll
;         for (int j = 0; j < 4; ++j) bf0[j] = *(const bf16x8*)(sB + (wn * 64 + j * 16 + l15) * LSTR + quad * 8);
; #pragma unroll
;         for (int i = 0; i < 4; ++i) af1[i] = *(const bf16x8*)(sA + (wm * 64 + i * 16 + l15) * LSTR + 32 + quad * 8);
; #pragma unroll
;         for (int j = 0; j < 4; ++j) bf1[j] = *(const bf16x8*)(sB + (wn * 64 + j * 16 + l15) * LSTR + 32 + quad * 8);
;         __builtin_amdgcn_sched_barrier(0);
;         if (kt + 1 < nk) GEMM_LOAD(ra0, ra1, ra2, ra3, rb0, rb1, rb2, rb3, (kt + 1) * 64)
;         __builtin_amdgcn_sched_barrier(0);
; #pragma unroll
;         for (int i = 0; i < 4; ++i)
; #pragma unroll
;           for (int j = 0; j < 4; ++j) acc[i][j] = __builtin_amdgcn_mfma_f32_16x16x32_bf16(bf0[j], af0[i], acc[i][j], 0, 0, 0);
; #pragma unroll
;         for (int i = 0; i < 4; ++i)
; #pragma unroll
;           for (int j = 0; j < 4; ++j) acc[i][j] = __builtin_amdgcn_mfma_f32_16x16x32_bf16(bf1[j], af1[i], acc[i][j], 0, 0, 0);
;         __builtin_amdgcn_s_setprio(0);
.LBB0_437:
	s_waitcnt lgkmcnt(14)
	v_mfma_f32_16x16x32_bf16 v[60:63], v[136:139], v[156:159], v[60:63]
	s_waitcnt lgkmcnt(13)
	v_mfma_f32_16x16x32_bf16 v[56:59], v[140:143], v[156:159], v[56:59]
	s_waitcnt lgkmcnt(12)
	v_mfma_f32_16x16x32_bf16 v[52:55], v[144:147], v[156:159], v[52:55]
	s_waitcnt lgkmcnt(11)
	v_mfma_f32_16x16x32_bf16 v[48:51], v[148:151], v[156:159], v[48:51]
	s_waitcnt lgkmcnt(10)
	v_mfma_f32_16x16x32_bf16 v[44:47], v[136:139], v[152:155], v[44:47]
	v_mfma_f32_16x16x32_bf16 v[40:43], v[140:143], v[152:155], v[40:43]
	v_mfma_f32_16x16x32_bf16 v[36:39], v[144:147], v[152:155], v[36:39]
	v_mfma_f32_16x16x32_bf16 v[32:35], v[148:151], v[152:155], v[32:35]
	s_waitcnt lgkmcnt(9)
	v_mfma_f32_16x16x32_bf16 v[28:31], v[136:139], v[132:135], v[28:31]
	v_mfma_f32_16x16x32_bf16 v[24:27], v[140:143], v[132:135], v[24:27]
	v_mfma_f32_16x16x32_bf16 v[20:23], v[144:147], v[132:135], v[20:23]
	v_mfma_f32_16x16x32_bf16 v[16:19], v[148:151], v[132:135], v[16:19]
	s_waitcnt lgkmcnt(8)
	v_mfma_f32_16x16x32_bf16 v[12:15], v[136:139], v[124:127], v[12:15]
	v_mfma_f32_16x16x32_bf16 v[8:11], v[140:143], v[124:127], v[8:11]
	v_mfma_f32_16x16x32_bf16 v[4:7], v[144:147], v[124:127], v[4:7]
	v_mfma_f32_16x16x32_bf16 v[0:3], v[148:151], v[124:127], v[0:3]
	s_waitcnt lgkmcnt(6)
	v_mfma_f32_16x16x32_bf16 v[60:63], v[104:107], v[128:131], v[60:63]
	s_waitcnt lgkmcnt(5)
	v_mfma_f32_16x16x32_bf16 v[56:59], v[108:111], v[128:131], v[56:59]
	s_waitcnt lgkmcnt(4)
	v_mfma_f32_16x16x32_bf16 v[52:55], v[112:115], v[128:131], v[52:55]
	s_waitcnt lgkmcnt(3)
	v_mfma_f32_16x16x32_bf16 v[48:51], v[116:119], v[128:131], v[48:51]
	s_waitcnt lgkmcnt(2)
	v_mfma_f32_16x16x32_bf16 v[44:47], v[104:107], v[120:123], v[44:47]
	v_mfma_f32_16x16x32_bf16 v[40:43], v[108:111], v[120:123], v[40:43]
	v_mfma_f32_16x16x32_bf16 v[36:39], v[112:115], v[120:123], v[36:39]
	v_mfma_f32_16x16x32_bf16 v[32:35], v[116:119], v[120:123], v[32:35]
	s_waitcnt lgkmcnt(1)
	v_mfma_f32_16x16x32_bf16 v[28:31], v[104:107], v[100:103], v[28:31]
	v_mfma_f32_16x16x32_bf16 v[24:27], v[108:111], v[100:103], v[24:27]
	v_mfma_f32_16x16x32_bf16 v[20:23], v[112:115], v[100:103], v[20:23]
	v_mfma_f32_16x16x32_bf16 v[16:19], v[116:119], v[100:103], v[16:19]
	s_waitcnt lgkmcnt(0)
	v_mfma_f32_16x16x32_bf16 v[12:15], v[104:107], v[96:99], v[12:15]
	v_mfma_f32_16x16x32_bf16 v[8:11], v[108:111], v[96:99], v[8:11]
	v_mfma_f32_16x16x32_bf16 v[4:7], v[112:115], v[96:99], v[4:7]
	v_mfma_f32_16x16x32_bf16 v[0:3], v[116:119], v[96:99], v[0:3]
	s_setprio 0
	s_add_u32 s12, s12, 0x80
	s_addc_u32 s13, s13, 0
	s_add_i32 s1, s1, 1
	s_cmpk_eq_i32 s12, 0x800
	s_cbranch_scc1 .LBB0_440
.LBB0_438:
	s_waitcnt vmcnt(63) expcnt(7) lgkmcnt(15)
	s_barrier
	s_waitcnt vmcnt(0)
	ds_write_b128 v161, v[64:67]
	ds_write_b128 v161, v[68:71] offset:5120
	ds_write_b128 v161, v[80:83] offset:10240
	ds_write_b128 v161, v[88:91] offset:15360
	ds_write_b128 v161, v[72:75] offset:20480
	ds_write_b128 v161, v[76:79] offset:25600
	ds_write_b128 v161, v[84:87] offset:30720
	ds_write_b128 v161, v[92:95] offset:35840
	s_waitcnt lgkmcnt(0)
	s_barrier
	s_setprio 1
	v_add_u32_e32 v96, v175, v178
	ds_read_b128 v[156:159], v96
	ds_read_b128 v[136:139], v180 offset:20480
	ds_read_b128 v[140:143], v180 offset:23040
	ds_read_b128 v[144:147], v180 offset:25600
	ds_read_b128 v[148:151], v180 offset:28160
	ds_read_b128 v[152:155], v96 offset:2560
	ds_read_b128 v[132:135], v96 offset:5120
	ds_read_b128 v[124:127], v96 offset:7680
	ds_read_b128 v[128:131], v182 offset:64
	ds_read_b128 v[104:107], v183 offset:20544
	ds_read_b128 v[108:111], v183 offset:23104
	ds_read_b128 v[112:115], v183 offset:25664
	ds_read_b128 v[116:119], v183 offset:28224
	ds_read_b128 v[120:123], v182 offset:2624
	ds_read_b128 v[100:103], v182 offset:5184
	ds_read_b128 v[96:99], v182 offset:7744
	s_cmp_gt_u32 s1, 14
	s_cbranch_scc1 .LBB0_437
	v_lshl_add_u64 v[72:73], v[170:171], 0, s[12:13]
	v_add_co_u32_e32 v64, vcc, 0x1d00000, v72
	v_lshl_add_u64 v[84:85], v[172:173], 0, s[12:13]
	s_nop 0
	v_addc_co_u32_e32 v65, vcc, 0, v73, vcc
	v_add_co_u32_e32 v68, vcc, 0x1d10000, v72
	s_nop 1
	v_addc_co_u32_e32 v69, vcc, 0, v73, vcc
	v_add_co_u32_e32 v74, vcc, 0x1d20000, v72
	global_load_dwordx4 v[64:67], v[64:65], off offset:128
	s_nop 0
	global_load_dwordx4 v[68:71], v[68:69], off offset:128
	v_addc_co_u32_e32 v75, vcc, 0, v73, vcc
	v_add_co_u32_e32 v72, vcc, 0x1d30000, v72
	s_nop 1
	v_addc_co_u32_e32 v73, vcc, 0, v73, vcc
	global_load_dwordx4 v[80:83], v[74:75], off offset:128
	global_load_dwordx4 v[88:91], v[72:73], off offset:128
	v_add_co_u32_e32 v72, vcc, 0x680000, v84
	s_nop 1
	v_addc_co_u32_e32 v73, vcc, 0, v85, vcc
	v_add_co_u32_e32 v76, vcc, 0x690000, v84
	s_nop 1
	v_addc_co_u32_e32 v77, vcc, 0, v85, vcc
	v_add_co_u32_e32 v86, vcc, 0x6a0000, v84
	global_load_dwordx4 v[72:75], v[72:73], off offset:128
	s_nop 0
	global_load_dwordx4 v[76:79], v[76:77], off offset:128
	v_addc_co_u32_e32 v87, vcc, 0, v85, vcc
	v_add_co_u32_e32 v92, vcc, 0x6b0000, v84
	s_nop 1
	v_addc_co_u32_e32 v93, vcc, 0, v85, vcc
	global_load_dwordx4 v[84:87], v[86:87], off offset:128
	s_nop 0
	global_load_dwordx4 v[92:95], v[92:93], off offset:128
	s_branch .LBB0_437

; template <bool DEEP, class Epi>
; __device__ __forceinline__ void gemm_phase(const bf16_t* __restrict__ A, int lda, const bf16_t* __restrict__ Wt,
;                                            int K, int ntn, bool lat_only, const Epi& epi, char* smem) {
;     ...
;     for (int kt = 0; kt < nk; ++kt) {
;       __syncthreads();
;       GEMM_STORE(ra0, ra1, ra2, ra3, rb0, rb1, rb2, rb3, 0)
;       __syncthreads();
;       {
;         bf16x8 af0[4], bf0[4], af1[4], bf1[4];
;         __builtin_amdgcn_s_setprio(1);
; #pragma unroll
;         for (int i = 0; i < 4; ++i) af0[i] = *(const bf16x8*)(sA + (wm * 64 + i * 16 + l15) * LSTR + quad * 8);
; #pragma unroll
;         for (int j = 0; j < 4; ++j) bf0[j] = *(const bf16x8*)(sB + (wn * 64 + j * 16 + l15) * LSTR + quad * 8);
; #pragma unroll
;         for (int i = 0; i < 4; ++i) af1[i] = *(const bf16x8*)(sA + (wm * 64 + i * 16 + l15) * LSTR + 32 + quad * 8);
; #pragma unroll
;         for (int j = 0; j < 4; ++j) bf1[j] = *(const bf16x8*)(sB + (wn * 64 + j * 16 + l15) * LSTR + 32 + quad * 8);
;         __builtin_amdgcn_sched_barrier(0);
;         if (kt + 1 < nk) GEMM_LOAD(ra0, ra1, ra2, ra3, rb0, rb1, rb2, rb3, (kt + 1) * 64)
;         __builtin_amdgcn_sched_barrier(0);
; #pragma unroll
;         for (int i = 0; i < 4; ++i)
; #pragma unroll
;           for (int j = 0; j < 4; ++j) acc[i][j] = __builtin_amdgcn_mfma_f32_16x16x32_bf16(bf0[j], af0[i], acc[i][j], 0, 0, 0);
; #pragma unroll
;         for (int i = 0; i < 4; ++i)
; #pragma unroll
;           for (int j = 0; j < 4; ++j) acc[i][j] = __builtin_amdgcn_mfma_f32_16x16x32_bf16(bf1[j], af1[i], acc[i][j], 0, 0, 0);
;         __builtin_amdgcn_s_setprio(0);
.LBB0_575:
	s_waitcnt lgkmcnt(14)
	v_mfma_f32_16x16x32_bf16 v[64:67], v[136:139], v[156:159], v[64:67]
	s_waitcnt lgkmcnt(13)
	v_mfma_f32_16x16x32_bf16 v[48:51], v[140:143], v[156:159], v[48:51]
	s_waitcnt lgkmcnt(12)
	v_mfma_f32_16x16x32_bf16 v[72:75], v[144:147], v[156:159], v[72:75]
	s_waitcnt lgkmcnt(11)
	v_mfma_f32_16x16x32_bf16 v[52:55], v[148:151], v[156:159], v[52:55]
	s_waitcnt lgkmcnt(10)
	v_mfma_f32_16x16x32_bf16 v[40:43], v[136:139], v[152:155], v[40:43]
	v_mfma_f32_16x16x32_bf16 v[32:35], v[140:143], v[152:155], v[32:35]
	v_mfma_f32_16x16x32_bf16 v[44:47], v[144:147], v[152:155], v[44:47]
	v_mfma_f32_16x16x32_bf16 v[36:39], v[148:151], v[152:155], v[36:39]
	s_waitcnt lgkmcnt(9)
	v_mfma_f32_16x16x32_bf16 v[24:27], v[136:139], v[132:135], v[24:27]
	v_mfma_f32_16x16x32_bf16 v[16:19], v[140:143], v[132:135], v[16:19]
	v_mfma_f32_16x16x32_bf16 v[28:31], v[144:147], v[132:135], v[28:31]
	v_mfma_f32_16x16x32_bf16 v[20:23], v[148:151], v[132:135], v[20:23]
	s_waitcnt lgkmcnt(8)
	v_mfma_f32_16x16x32_bf16 v[8:11], v[136:139], v[124:127], v[8:11]
	v_mfma_f32_16x16x32_bf16 v[0:3], v[140:143], v[124:127], v[0:3]
	v_mfma_f32_16x16x32_bf16 v[12:15], v[144:147], v[124:127], v[12:15]
	v_mfma_f32_16x16x32_bf16 v[4:7], v[148:151], v[124:127], v[4:7]
	s_waitcnt lgkmcnt(6)
	v_mfma_f32_16x16x32_bf16 v[64:67], v[104:107], v[128:131], v[64:67]
	s_waitcnt lgkmcnt(5)
	v_mfma_f32_16x16x32_bf16 v[48:51], v[108:111], v[128:131], v[48:51]
	s_waitcnt lgkmcnt(4)
	v_mfma_f32_16x16x32_bf16 v[72:75], v[112:115], v[128:131], v[72:75]
	s_waitcnt lgkmcnt(3)
	v_mfma_f32_16x16x32_bf16 v[52:55], v[116:119], v[128:131], v[52:55]
	s_waitcnt lgkmcnt(2)
	v_mfma_f32_16x16x32_bf16 v[40:43], v[104:107], v[120:123], v[40:43]
	v_mfma_f32_16x16x32_bf16 v[32:35], v[108:111], v[120:123], v[32:35]
	v_mfma_f32_16x16x32_bf16 v[44:47], v[112:115], v[120:123], v[44:47]
	v_mfma_f32_16x16x32_bf16 v[36:39], v[116:119], v[120:123], v[36:39]
	s_waitcnt lgkmcnt(1)
	v_mfma_f32_16x16x32_bf16 v[24:27], v[104:107], v[100:103], v[24:27]
	v_mfma_f32_16x16x32_bf16 v[16:19], v[108:111], v[100:103], v[16:19]
	v_mfma_f32_16x16x32_bf16 v[28:31], v[112:115], v[100:103], v[28:31]
	v_mfma_f32_16x16x32_bf16 v[20:23], v[116:119], v[100:103], v[20:23]
	s_waitcnt lgkmcnt(0)
	v_mfma_f32_16x16x32_bf16 v[8:11], v[104:107], v[96:99], v[8:11]
	v_mfma_f32_16x16x32_bf16 v[0:3], v[108:111], v[96:99], v[0:3]
	v_mfma_f32_16x16x32_bf16 v[12:15], v[112:115], v[96:99], v[12:15]
	v_mfma_f32_16x16x32_bf16 v[4:7], v[116:119], v[96:99], v[4:7]
	s_setprio 0
	s_add_u32 s8, s8, 0x80
	s_addc_u32 s9, s9, 0
	s_cmpk_eq_i32 s8, 0x800
	s_cbranch_scc1 .LBB0_573
.LBB0_576:
	s_waitcnt vmcnt(63) expcnt(7) lgkmcnt(15)
	s_barrier
	s_waitcnt vmcnt(7)
	ds_write_b128 v176, v[56:59]
	s_waitcnt vmcnt(6)
	ds_write_b128 v176, v[60:63] offset:5120
	s_waitcnt vmcnt(5)
	ds_write_b128 v176, v[68:71] offset:10240
	s_waitcnt vmcnt(4)
	ds_write_b128 v176, v[76:79] offset:15360
	s_waitcnt vmcnt(3)
	ds_write_b128 v176, v[80:83] offset:20480
	s_waitcnt vmcnt(2)
	ds_write_b128 v176, v[84:87] offset:25600
	s_waitcnt vmcnt(1)
	ds_write_b128 v176, v[88:91] offset:30720
	s_waitcnt vmcnt(0)
	ds_write_b128 v176, v[92:95] offset:35840
	s_waitcnt lgkmcnt(0)
	s_barrier
	s_setprio 1
	v_add_u32_e32 v96, v180, v182
	ds_read_b128 v[156:159], v96
	ds_read_b128 v[136:139], v183 offset:20480
	ds_read_b128 v[140:143], v183 offset:23040
	ds_read_b128 v[144:147], v183 offset:25600
	ds_read_b128 v[148:151], v183 offset:28160
	ds_read_b128 v[152:155], v96 offset:2560
	ds_read_b128 v[132:135], v96 offset:5120
	ds_read_b128 v[124:127], v96 offset:7680
	ds_read_b128 v[128:131], v184 offset:64
	ds_read_b128 v[104:107], v185 offset:20544
	ds_read_b128 v[108:111], v185 offset:23104
	ds_read_b128 v[112:115], v185 offset:25664
	ds_read_b128 v[116:119], v185 offset:28224
	ds_read_b128 v[120:123], v184 offset:2624
	ds_read_b128 v[100:103], v184 offset:5184
	ds_read_b128 v[96:99], v184 offset:7744
	s_cmpk_eq_i32 s8, 0x780
	s_cbranch_scc1 .LBB0_575
	v_lshl_add_u64 v[68:69], v[172:173], 0, s[8:9]
	v_add_co_u32_e32 v56, vcc, 0x1d00000, v68
	v_lshl_add_u64 v[88:89], v[174:175], 0, s[8:9]
	s_nop 0
	v_addc_co_u32_e32 v57, vcc, 0, v69, vcc
	v_add_co_u32_e32 v60, vcc, 0x1d10000, v68
	s_nop 1
	v_addc_co_u32_e32 v61, vcc, 0, v69, vcc
	v_add_co_u32_e32 v70, vcc, 0x1d20000, v68
	global_load_dwordx4 v[56:59], v[56:57], off offset:128
	s_nop 0
	global_load_dwordx4 v[60:63], v[60:61], off offset:128
	v_addc_co_u32_e32 v71, vcc, 0, v69, vcc
	v_add_co_u32_e32 v76, vcc, 0x1d30000, v68
	s_nop 1
	v_addc_co_u32_e32 v77, vcc, 0, v69, vcc
	v_add_co_u32_e32 v80, vcc, 0x880000, v88
	global_load_dwordx4 v[68:71], v[70:71], off offset:128
	s_nop 0
	global_load_dwordx4 v[76:79], v[76:77], off offset:128
	v_addc_co_u32_e32 v81, vcc, 0, v89, vcc
	v_add_co_u32_e32 v84, vcc, 0x890000, v88
	s_nop 1
	v_addc_co_u32_e32 v85, vcc, 0, v89, vcc
	v_add_co_u32_e32 v90, vcc, 0x8a0000, v88
	global_load_dwordx4 v[80:83], v[80:81], off offset:128
	s_nop 0
	global_load_dwordx4 v[84:87], v[84:85], off offset:128
	v_addc_co_u32_e32 v91, vcc, 0, v89, vcc
	v_add_co_u32_e32 v92, vcc, 0x8b0000, v88
	s_nop 1
	v_addc_co_u32_e32 v93, vcc, 0, v89, vcc
	global_load_dwordx4 v[88:91], v[90:91], off offset:128
	s_nop 0
	global_load_dwordx4 v[92:95], v[92:93], off offset:128
	s_branch .LBB0_575

; template <bool DEEP, class Epi>
; __device__ __forceinline__ void gemm_phase(const bf16_t* __restrict__ A, int lda, const bf16_t* __restrict__ Wt,
;                                            int K, int ntn, bool lat_only, const Epi& epi, char* smem) {
;     ...
;     for (int kt = 0; kt < nk; ++kt) {
;       __syncthreads();
;       GEMM_STORE(ra0, ra1, ra2, ra3, rb0, rb1, rb2, rb3, 0)
;       __syncthreads();
;       {
;         bf16x8 af0[4], bf0[4], af1[4], bf1[4];
;         __builtin_amdgcn_s_setprio(1);
; #pragma unroll
;         for (int i = 0; i < 4; ++i) af0[i] = *(const bf16x8*)(sA + (wm * 64 + i * 16 + l15) * LSTR + quad * 8);
; #pragma unroll
;         for (int j = 0; j < 4; ++j) bf0[j] = *(const bf16x8*)(sB + (wn * 64 + j * 16 + l15) * LSTR + quad * 8);
; #pragma unroll
;         for (int i = 0; i < 4; ++i) af1[i] = *(const bf16x8*)(sA + (wm * 64 + i * 16 + l15) * LSTR + 32 + quad * 8);
; #pragma unroll
;         for (int j = 0; j < 4; ++j) bf1[j] = *(const bf16x8*)(sB + (wn * 64 + j * 16 + l15) * LSTR + 32 + quad * 8);
;         __builtin_amdgcn_sched_barrier(0);
;         if (kt + 1 < nk) GEMM_LOAD(ra0, ra1, ra2, ra3, rb0, rb1, rb2, rb3, (kt + 1) * 64)
;         __builtin_amdgcn_sched_barrier(0);
; #pragma unroll
;         for (int i = 0; i < 4; ++i)
; #pragma unroll
;           for (int j = 0; j < 4; ++j) acc[i][j] = __builtin_amdgcn_mfma_f32_16x16x32_bf16(bf0[j], af0[i], acc[i][j], 0, 0, 0);
; #pragma unroll
;         for (int i = 0; i < 4; ++i)
; #pragma unroll
;           for (int j = 0; j < 4; ++j) acc[i][j] = __builtin_amdgcn_mfma_f32_16x16x32_bf16(bf1[j], af1[i], acc[i][j], 0, 0, 0);
;         __builtin_amdgcn_s_setprio(0);
.LBB0_634:
	s_waitcnt lgkmcnt(14)
	v_mfma_f32_16x16x32_bf16 v[60:63], v[136:139], v[156:159], v[60:63]
	s_waitcnt lgkmcnt(13)
	v_mfma_f32_16x16x32_bf16 v[56:59], v[140:143], v[156:159], v[56:59]
	s_waitcnt lgkmcnt(12)
	v_mfma_f32_16x16x32_bf16 v[52:55], v[144:147], v[156:159], v[52:55]
	s_waitcnt lgkmcnt(11)
	v_mfma_f32_16x16x32_bf16 v[48:51], v[148:151], v[156:159], v[48:51]
	s_waitcnt lgkmcnt(10)
	v_mfma_f32_16x16x32_bf16 v[44:47], v[136:139], v[152:155], v[44:47]
	v_mfma_f32_16x16x32_bf16 v[40:43], v[140:143], v[152:155], v[40:43]
	v_mfma_f32_16x16x32_bf16 v[36:39], v[144:147], v[152:155], v[36:39]
	v_mfma_f32_16x16x32_bf16 v[32:35], v[148:151], v[152:155], v[32:35]
	s_waitcnt lgkmcnt(9)
	v_mfma_f32_16x16x32_bf16 v[28:31], v[136:139], v[132:135], v[28:31]
	v_mfma_f32_16x16x32_bf16 v[24:27], v[140:143], v[132:135], v[24:27]
	v_mfma_f32_16x16x32_bf16 v[20:23], v[144:147], v[132:135], v[20:23]
	v_mfma_f32_16x16x32_bf16 v[16:19], v[148:151], v[132:135], v[16:19]
	s_waitcnt lgkmcnt(8)
	v_mfma_f32_16x16x32_bf16 v[12:15], v[136:139], v[124:127], v[12:15]
	v_mfma_f32_16x16x32_bf16 v[8:11], v[140:143], v[124:127], v[8:11]
	v_mfma_f32_16x16x32_bf16 v[4:7], v[144:147], v[124:127], v[4:7]
	v_mfma_f32_16x16x32_bf16 v[0:3], v[148:151], v[124:127], v[0:3]
	s_waitcnt lgkmcnt(6)
	v_mfma_f32_16x16x32_bf16 v[60:63], v[104:107], v[128:131], v[60:63]
	s_waitcnt lgkmcnt(5)
	v_mfma_f32_16x16x32_bf16 v[56:59], v[108:111], v[128:131], v[56:59]
	s_waitcnt lgkmcnt(4)
	v_mfma_f32_16x16x32_bf16 v[52:55], v[112:115], v[128:131], v[52:55]
	s_waitcnt lgkmcnt(3)
	v_mfma_f32_16x16x32_bf16 v[48:51], v[116:119], v[128:131], v[48:51]
	s_waitcnt lgkmcnt(2)
	v_mfma_f32_16x16x32_bf16 v[44:47], v[104:107], v[120:123], v[44:47]
	v_mfma_f32_16x16x32_bf16 v[40:43], v[108:111], v[120:123], v[40:43]
	v_mfma_f32_16x16x32_bf16 v[36:39], v[112:115], v[120:123], v[36:39]
	v_mfma_f32_16x16x32_bf16 v[32:35], v[116:119], v[120:123], v[32:35]
	s_waitcnt lgkmcnt(1)
	v_mfma_f32_16x16x32_bf16 v[28:31], v[104:107], v[100:103], v[28:31]
	v_mfma_f32_16x16x32_bf16 v[24:27], v[108:111], v[100:103], v[24:27]
	v_mfma_f32_16x16x32_bf16 v[20:23], v[112:115], v[100:103], v[20:23]
	v_mfma_f32_16x16x32_bf16 v[16:19], v[116:119], v[100:103], v[16:19]
	s_waitcnt lgkmcnt(0)
	v_mfma_f32_16x16x32_bf16 v[12:15], v[104:107], v[96:99], v[12:15]
	v_mfma_f32_16x16x32_bf16 v[8:11], v[108:111], v[96:99], v[8:11]
	v_mfma_f32_16x16x32_bf16 v[4:7], v[112:115], v[96:99], v[4:7]
	v_mfma_f32_16x16x32_bf16 v[0:3], v[116:119], v[96:99], v[0:3]
	s_setprio 0
	s_add_u32 s0, s0, 0x80
	s_addc_u32 s1, s1, 0
	s_add_i32 s15, s15, 1
	s_cmpk_eq_i32 s0, 0x1600
	s_cbranch_scc1 .LBB0_637
.LBB0_635:
	s_waitcnt vmcnt(63) expcnt(7) lgkmcnt(15)
	s_barrier
	s_waitcnt vmcnt(0)
	ds_write_b128 v161, v[64:67]
	ds_write_b128 v161, v[68:71] offset:5120
	ds_write_b128 v161, v[80:83] offset:10240
	ds_write_b128 v161, v[88:91] offset:15360
	ds_write_b128 v161, v[72:75] offset:20480
	ds_write_b128 v161, v[76:79] offset:25600
	ds_write_b128 v161, v[84:87] offset:30720
	ds_write_b128 v161, v[92:95] offset:35840
	s_waitcnt lgkmcnt(0)
	s_barrier
	s_setprio 1
	v_add_u32_e32 v96, v175, v178
	ds_read_b128 v[156:159], v96
	ds_read_b128 v[136:139], v182 offset:20480
	ds_read_b128 v[140:143], v182 offset:23040
	ds_read_b128 v[144:147], v182 offset:25600
	ds_read_b128 v[148:151], v182 offset:28160
	ds_read_b128 v[152:155], v96 offset:2560
	ds_read_b128 v[132:135], v96 offset:5120
	ds_read_b128 v[124:127], v96 offset:7680
	ds_read_b128 v[128:131], v183 offset:64
	ds_read_b128 v[104:107], v184 offset:20544
	ds_read_b128 v[108:111], v184 offset:23104
	ds_read_b128 v[112:115], v184 offset:25664
	ds_read_b128 v[116:119], v184 offset:28224
	ds_read_b128 v[120:123], v183 offset:2624
	ds_read_b128 v[100:103], v183 offset:5184
	ds_read_b128 v[96:99], v183 offset:7744
	s_cmp_gt_u32 s15, 42
	s_cbranch_scc1 .LBB0_634
	v_lshl_add_u64 v[72:73], v[170:171], 0, s[0:1]
	v_add_co_u32_e32 v64, vcc, 0x5e00000, v72
	v_lshl_add_u64 v[84:85], v[172:173], 0, s[0:1]
	s_nop 0
	v_addc_co_u32_e32 v65, vcc, 0, v73, vcc
	v_add_co_u32_e32 v68, vcc, 0x5e2c000, v72
	s_nop 1
	v_addc_co_u32_e32 v69, vcc, 0, v73, vcc
	v_add_co_u32_e32 v74, vcc, 0x5e58000, v72
	global_load_dwordx4 v[64:67], v[64:65], off offset:128
	s_nop 0
	global_load_dwordx4 v[68:71], v[68:69], off offset:128
	v_addc_co_u32_e32 v75, vcc, 0, v73, vcc
	v_add_co_u32_e32 v72, vcc, 0x5e84000, v72
	s_nop 1
	v_addc_co_u32_e32 v73, vcc, 0, v73, vcc
	global_load_dwordx4 v[80:83], v[74:75], off offset:128
	global_load_dwordx4 v[88:91], v[72:73], off offset:128
	v_add_co_u32_e32 v72, vcc, 0x1380000, v84
	s_nop 1
	v_addc_co_u32_e32 v73, vcc, 0, v85, vcc
	v_add_co_u32_e32 v76, vcc, 0x13ac000, v84
	s_nop 1
	v_addc_co_u32_e32 v77, vcc, 0, v85, vcc
	v_add_co_u32_e32 v86, vcc, 0x13d8000, v84
	global_load_dwordx4 v[72:75], v[72:73], off offset:128
	s_nop 0
	global_load_dwordx4 v[76:79], v[76:77], off offset:128
	v_addc_co_u32_e32 v87, vcc, 0, v85, vcc
	v_add_co_u32_e32 v92, vcc, 0x1404000, v84
	s_nop 1
	v_addc_co_u32_e32 v93, vcc, 0, v85, vcc
	global_load_dwordx4 v[84:87], v[86:87], off offset:128
	s_nop 0
	global_load_dwordx4 v[92:95], v[92:93], off offset:128
	s_branch .LBB0_634

; template <bool DEEP, class Epi>
; __device__ __forceinline__ void gemm_phase(const bf16_t* __restrict__ A, int lda, const bf16_t* __restrict__ Wt,
;                                            int K, int ntn, bool lat_only, const Epi& epi, char* smem) {
;     ...
;     for (int kt = 0; kt < nk; ++kt) {
;       __syncthreads();
;       GEMM_STORE(ra0, ra1, ra2, ra3, rb0, rb1, rb2, rb3, 0)
;       __syncthreads();
;       {
;         bf16x8 af0[4], bf0[4], af1[4], bf1[4];
;         __builtin_amdgcn_s_setprio(1);
; #pragma unroll
;         for (int i = 0; i < 4; ++i) af0[i] = *(const bf16x8*)(sA + (wm * 64 + i * 16 + l15) * LSTR + quad * 8);
; #pragma unroll
;         for (int j = 0; j < 4; ++j) bf0[j] = *(const bf16x8*)(sB + (wn * 64 + j * 16 + l15) * LSTR + quad * 8);
; #pragma unroll
;         for (int i = 0; i < 4; ++i) af1[i] = *(const bf16x8*)(sA + (wm * 64 + i * 16 + l15) * LSTR + 32 + quad * 8);
; #pragma unroll
;         for (int j = 0; j < 4; ++j) bf1[j] = *(const bf16x8*)(sB + (wn * 64 + j * 16 + l15) * LSTR + 32 + quad * 8);
;         __builtin_amdgcn_sched_barrier(0);
;         if (kt + 1 < nk) GEMM_LOAD(ra0, ra1, ra2, ra3, rb0, rb1, rb2, rb3, (kt + 1) * 64)
;         __builtin_amdgcn_sched_barrier(0);
; #pragma unroll
;         for (int i = 0; i < 4; ++i)
; #pragma unroll
;           for (int j = 0; j < 4; ++j) acc[i][j] = __builtin_amdgcn_mfma_f32_16x16x32_bf16(bf0[j], af0[i], acc[i][j], 0, 0, 0);
; #pragma unroll
;         for (int i = 0; i < 4; ++i)
; #pragma unroll
;           for (int j = 0; j < 4; ++j) acc[i][j] = __builtin_amdgcn_mfma_f32_16x16x32_bf16(bf1[j], af1[i], acc[i][j], 0, 0, 0);
;         __builtin_amdgcn_s_setprio(0);
.LBB0_847:
	s_waitcnt lgkmcnt(14)
	v_mfma_f32_16x16x32_bf16 v[60:63], v[136:139], v[156:159], v[60:63]
	s_waitcnt lgkmcnt(13)
	v_mfma_f32_16x16x32_bf16 v[56:59], v[140:143], v[156:159], v[56:59]
	s_waitcnt lgkmcnt(12)
	v_mfma_f32_16x16x32_bf16 v[52:55], v[144:147], v[156:159], v[52:55]
	s_waitcnt lgkmcnt(11)
	v_mfma_f32_16x16x32_bf16 v[48:51], v[148:151], v[156:159], v[48:51]
	s_waitcnt lgkmcnt(10)
	v_mfma_f32_16x16x32_bf16 v[44:47], v[136:139], v[152:155], v[44:47]
	v_mfma_f32_16x16x32_bf16 v[40:43], v[140:143], v[152:155], v[40:43]
	v_mfma_f32_16x16x32_bf16 v[36:39], v[144:147], v[152:155], v[36:39]
	v_mfma_f32_16x16x32_bf16 v[32:35], v[148:151], v[152:155], v[32:35]
	s_waitcnt lgkmcnt(9)
	v_mfma_f32_16x16x32_bf16 v[28:31], v[136:139], v[132:135], v[28:31]
	v_mfma_f32_16x16x32_bf16 v[24:27], v[140:143], v[132:135], v[24:27]
	v_mfma_f32_16x16x32_bf16 v[20:23], v[144:147], v[132:135], v[20:23]
	v_mfma_f32_16x16x32_bf16 v[16:19], v[148:151], v[132:135], v[16:19]
	s_waitcnt lgkmcnt(8)
	v_mfma_f32_16x16x32_bf16 v[12:15], v[136:139], v[124:127], v[12:15]
	v_mfma_f32_16x16x32_bf16 v[8:11], v[140:143], v[124:127], v[8:11]
	v_mfma_f32_16x16x32_bf16 v[4:7], v[144:147], v[124:127], v[4:7]
	v_mfma_f32_16x16x32_bf16 v[0:3], v[148:151], v[124:127], v[0:3]
	s_waitcnt lgkmcnt(6)
	v_mfma_f32_16x16x32_bf16 v[60:63], v[104:107], v[128:131], v[60:63]
	s_waitcnt lgkmcnt(5)
	v_mfma_f32_16x16x32_bf16 v[56:59], v[108:111], v[128:131], v[56:59]
	s_waitcnt lgkmcnt(4)
	v_mfma_f32_16x16x32_bf16 v[52:55], v[112:115], v[128:131], v[52:55]
	s_waitcnt lgkmcnt(3)
	v_mfma_f32_16x16x32_bf16 v[48:51], v[116:119], v[128:131], v[48:51]
	s_waitcnt lgkmcnt(2)
	v_mfma_f32_16x16x32_bf16 v[44:47], v[104:107], v[120:123], v[44:47]
	v_mfma_f32_16x16x32_bf16 v[40:43], v[108:111], v[120:123], v[40:43]
	v_mfma_f32_16x16x32_bf16 v[36:39], v[112:115], v[120:123], v[36:39]
	v_mfma_f32_16x16x32_bf16 v[32:35], v[116:119], v[120:123], v[32:35]
	s_waitcnt lgkmcnt(1)
	v_mfma_f32_16x16x32_bf16 v[28:31], v[104:107], v[100:103], v[28:31]
	v_mfma_f32_16x16x32_bf16 v[24:27], v[108:111], v[100:103], v[24:27]
	v_mfma_f32_16x16x32_bf16 v[20:23], v[112:115], v[100:103], v[20:23]
	v_mfma_f32_16x16x32_bf16 v[16:19], v[116:119], v[100:103], v[16:19]
	s_waitcnt lgkmcnt(0)
	v_mfma_f32_16x16x32_bf16 v[12:15], v[104:107], v[96:99], v[12:15]
	v_mfma_f32_16x16x32_bf16 v[8:11], v[108:111], v[96:99], v[8:11]
	v_mfma_f32_16x16x32_bf16 v[4:7], v[112:115], v[96:99], v[4:7]
	v_mfma_f32_16x16x32_bf16 v[0:3], v[116:119], v[96:99], v[0:3]
	s_setprio 0
	s_add_u32 s6, s6, 0x80
	s_addc_u32 s7, s7, 0
	s_cmpk_eq_i32 s6, 0x800
	s_cbranch_scc1 .LBB0_850
.LBB0_848:
	s_waitcnt vmcnt(63) expcnt(7) lgkmcnt(15)
	s_barrier
	s_waitcnt vmcnt(7)
	ds_write_b128 v173, v[64:67]
	s_waitcnt vmcnt(6)
	ds_write_b128 v173, v[68:71] offset:5120
	s_waitcnt vmcnt(5)
	ds_write_b128 v173, v[72:75] offset:10240
	s_waitcnt vmcnt(4)
	ds_write_b128 v173, v[76:79] offset:15360
	s_waitcnt vmcnt(3)
	ds_write_b128 v173, v[80:83] offset:20480
	s_waitcnt vmcnt(2)
	ds_write_b128 v173, v[84:87] offset:25600
	s_waitcnt vmcnt(1)
	ds_write_b128 v173, v[88:91] offset:30720
	s_waitcnt vmcnt(0)
	ds_write_b128 v173, v[92:95] offset:35840
	s_waitcnt lgkmcnt(0)
	s_barrier
	s_setprio 1
	v_add_u32_e32 v96, v183, v187
	ds_read_b128 v[156:159], v96
	ds_read_b128 v[136:139], v189 offset:20480
	ds_read_b128 v[140:143], v189 offset:23040
	ds_read_b128 v[144:147], v189 offset:25600
	ds_read_b128 v[148:151], v189 offset:28160
	ds_read_b128 v[152:155], v96 offset:2560
	ds_read_b128 v[132:135], v96 offset:5120
	ds_read_b128 v[124:127], v96 offset:7680
	ds_read_b128 v[128:131], v191 offset:64
	ds_read_b128 v[104:107], v193 offset:20544
	ds_read_b128 v[108:111], v193 offset:23104
	ds_read_b128 v[112:115], v193 offset:25664
	ds_read_b128 v[116:119], v193 offset:28224
	ds_read_b128 v[120:123], v191 offset:2624
	ds_read_b128 v[100:103], v191 offset:5184
	ds_read_b128 v[96:99], v191 offset:7744
	s_cmpk_eq_i32 s6, 0x780
	s_cbranch_scc1 .LBB0_847
	v_lshl_add_u64 v[72:73], v[204:205], 0, s[6:7]
	v_add_co_u32_e32 v64, vcc, 0x1d00000, v72
	v_lshl_add_u64 v[88:89], v[206:207], 0, s[6:7]
	s_nop 0
	v_addc_co_u32_e32 v65, vcc, 0, v73, vcc
	v_add_co_u32_e32 v68, vcc, 0x1d10000, v72
	s_nop 1
	v_addc_co_u32_e32 v69, vcc, 0, v73, vcc
	v_add_co_u32_e32 v74, vcc, 0x1d20000, v72
	global_load_dwordx4 v[64:67], v[64:65], off offset:128
	s_nop 0
	global_load_dwordx4 v[68:71], v[68:69], off offset:128
	v_addc_co_u32_e32 v75, vcc, 0, v73, vcc
	v_add_co_u32_e32 v76, vcc, 0x1d30000, v72
	s_nop 1
	v_addc_co_u32_e32 v77, vcc, 0, v73, vcc
	v_add_co_u32_e32 v84, vcc, 0x10000, v88
	global_load_dwordx4 v[72:75], v[74:75], off offset:128
	s_nop 0
	global_load_dwordx4 v[76:79], v[76:77], off offset:128
	v_addc_co_u32_e32 v85, vcc, 0, v89, vcc
	v_add_co_u32_e32 v90, vcc, 0x20000, v88
	global_load_dwordx4 v[80:83], v[88:89], off offset:128
	s_nop 0
	global_load_dwordx4 v[84:87], v[84:85], off offset:128
	v_addc_co_u32_e32 v91, vcc, 0, v89, vcc
	v_add_co_u32_e32 v92, vcc, 0x30000, v88
	s_nop 1
	v_addc_co_u32_e32 v93, vcc, 0, v89, vcc
	global_load_dwordx4 v[88:91], v[90:91], off offset:128
	s_nop 0
	global_load_dwordx4 v[92:95], v[92:93], off offset:128
	s_branch .LBB0_847

; template <bool DEEP, class Epi>
; __device__ __forceinline__ void gemm_phase(const bf16_t* __restrict__ A, int lda, const bf16_t* __restrict__ Wt,
;                                            int K, int ntn, bool lat_only, const Epi& epi, char* smem) {
;     ...
;     for (int kt = 0; kt < nk; ++kt) {
;       __syncthreads();
;       GEMM_STORE(ra0, ra1, ra2, ra3, rb0, rb1, rb2, rb3, 0)
;       __syncthreads();
;       {
;         bf16x8 af0[4], bf0[4], af1[4], bf1[4];
;         __builtin_amdgcn_s_setprio(1);
; #pragma unroll
;         for (int i = 0; i < 4; ++i) af0[i] = *(const bf16x8*)(sA + (wm * 64 + i * 16 + l15) * LSTR + quad * 8);
; #pragma unroll
;         for (int j = 0; j < 4; ++j) bf0[j] = *(const bf16x8*)(sB + (wn * 64 + j * 16 + l15) * LSTR + quad * 8);
; #pragma unroll
;         for (int i = 0; i < 4; ++i) af1[i] = *(const bf16x8*)(sA + (wm * 64 + i * 16 + l15) * LSTR + 32 + quad * 8);
; #pragma unroll
;         for (int j = 0; j < 4; ++j) bf1[j] = *(const bf16x8*)(sB + (wn * 64 + j * 16 + l15) * LSTR + 32 + quad * 8);
;         __builtin_amdgcn_sched_barrier(0);
;         if (kt + 1 < nk) GEMM_LOAD(ra0, ra1, ra2, ra3, rb0, rb1, rb2, rb3, (kt + 1) * 64)
;         __builtin_amdgcn_sched_barrier(0);
; #pragma unroll
;         for (int i = 0; i < 4; ++i)
; #pragma unroll
;           for (int j = 0; j < 4; ++j) acc[i][j] = __builtin_amdgcn_mfma_f32_16x16x32_bf16(bf0[j], af0[i], acc[i][j], 0, 0, 0);
; #pragma unroll
;         for (int i = 0; i < 4; ++i)
; #pragma unroll
;           for (int j = 0; j < 4; ++j) acc[i][j] = __builtin_amdgcn_mfma_f32_16x16x32_bf16(bf1[j], af1[i], acc[i][j], 0, 0, 0);
;         __builtin_amdgcn_s_setprio(0);
.LBB0_1420:
	s_waitcnt lgkmcnt(14)
	v_mfma_f32_16x16x32_bf16 v[60:63], v[136:139], v[156:159], v[60:63]
	s_waitcnt lgkmcnt(13)
	v_mfma_f32_16x16x32_bf16 v[56:59], v[140:143], v[156:159], v[56:59]
	s_waitcnt lgkmcnt(12)
	v_mfma_f32_16x16x32_bf16 v[52:55], v[144:147], v[156:159], v[52:55]
	s_waitcnt lgkmcnt(11)
	v_mfma_f32_16x16x32_bf16 v[48:51], v[148:151], v[156:159], v[48:51]
	s_waitcnt lgkmcnt(10)
	v_mfma_f32_16x16x32_bf16 v[44:47], v[136:139], v[152:155], v[44:47]
	v_mfma_f32_16x16x32_bf16 v[40:43], v[140:143], v[152:155], v[40:43]
	v_mfma_f32_16x16x32_bf16 v[36:39], v[144:147], v[152:155], v[36:39]
	v_mfma_f32_16x16x32_bf16 v[32:35], v[148:151], v[152:155], v[32:35]
	s_waitcnt lgkmcnt(9)
	v_mfma_f32_16x16x32_bf16 v[28:31], v[136:139], v[132:135], v[28:31]
	v_mfma_f32_16x16x32_bf16 v[24:27], v[140:143], v[132:135], v[24:27]
	v_mfma_f32_16x16x32_bf16 v[20:23], v[144:147], v[132:135], v[20:23]
	v_mfma_f32_16x16x32_bf16 v[16:19], v[148:151], v[132:135], v[16:19]
	s_waitcnt lgkmcnt(8)
	v_mfma_f32_16x16x32_bf16 v[12:15], v[136:139], v[124:127], v[12:15]
	v_mfma_f32_16x16x32_bf16 v[8:11], v[140:143], v[124:127], v[8:11]
	v_mfma_f32_16x16x32_bf16 v[4:7], v[144:147], v[124:127], v[4:7]
	v_mfma_f32_16x16x32_bf16 v[0:3], v[148:151], v[124:127], v[0:3]
	s_waitcnt lgkmcnt(6)
	v_mfma_f32_16x16x32_bf16 v[60:63], v[104:107], v[128:131], v[60:63]
	s_waitcnt lgkmcnt(5)
	v_mfma_f32_16x16x32_bf16 v[56:59], v[108:111], v[128:131], v[56:59]
	s_waitcnt lgkmcnt(4)
	v_mfma_f32_16x16x32_bf16 v[52:55], v[112:115], v[128:131], v[52:55]
	s_waitcnt lgkmcnt(3)
	v_mfma_f32_16x16x32_bf16 v[48:51], v[116:119], v[128:131], v[48:51]
	s_waitcnt lgkmcnt(2)
	v_mfma_f32_16x16x32_bf16 v[44:47], v[104:107], v[120:123], v[44:47]
	v_mfma_f32_16x16x32_bf16 v[40:43], v[108:111], v[120:123], v[40:43]
	v_mfma_f32_16x16x32_bf16 v[36:39], v[112:115], v[120:123], v[36:39]
	v_mfma_f32_16x16x32_bf16 v[32:35], v[116:119], v[120:123], v[32:35]
	s_waitcnt lgkmcnt(1)
	v_mfma_f32_16x16x32_bf16 v[28:31], v[104:107], v[100:103], v[28:31]
	v_mfma_f32_16x16x32_bf16 v[24:27], v[108:111], v[100:103], v[24:27]
	v_mfma_f32_16x16x32_bf16 v[20:23], v[112:115], v[100:103], v[20:23]
	v_mfma_f32_16x16x32_bf16 v[16:19], v[116:119], v[100:103], v[16:19]
	s_waitcnt lgkmcnt(0)
	v_mfma_f32_16x16x32_bf16 v[12:15], v[104:107], v[96:99], v[12:15]
	v_mfma_f32_16x16x32_bf16 v[8:11], v[108:111], v[96:99], v[8:11]
	v_mfma_f32_16x16x32_bf16 v[4:7], v[112:115], v[96:99], v[4:7]
	v_mfma_f32_16x16x32_bf16 v[0:3], v[116:119], v[96:99], v[0:3]
	s_setprio 0
	s_add_u32 s8, s8, 0x80
	s_addc_u32 s9, s9, 0
	s_add_i32 s1, s1, 1
	s_cmpk_eq_i32 s8, 0x800
	s_cbranch_scc1 .LBB0_1423
.LBB0_1421:
	s_barrier
	s_waitcnt vmcnt(0)
	ds_write_b128 v161, v[64:67]
	ds_write_b128 v161, v[68:71] offset:5120
	ds_write_b128 v161, v[76:79] offset:10240
	ds_write_b128 v161, v[84:87] offset:15360
	ds_write_b128 v161, v[72:75] offset:20480
	ds_write_b128 v161, v[80:83] offset:25600
	ds_write_b128 v161, v[88:91] offset:30720
	ds_write_b128 v161, v[92:95] offset:35840
	s_waitcnt lgkmcnt(0)
	s_barrier
	s_setprio 1
	v_add_u32_e32 v96, v173, v175
	ds_read_b128 v[156:159], v96
	ds_read_b128 v[136:139], v176 offset:20480
	ds_read_b128 v[140:143], v176 offset:23040
	ds_read_b128 v[144:147], v176 offset:25600
	ds_read_b128 v[148:151], v176 offset:28160
	ds_read_b128 v[152:155], v96 offset:2560
	ds_read_b128 v[132:135], v96 offset:5120
	ds_read_b128 v[124:127], v96 offset:7680
	ds_read_b128 v[128:131], v178 offset:64
	ds_read_b128 v[104:107], v179 offset:20544
	ds_read_b128 v[108:111], v179 offset:23104
	ds_read_b128 v[112:115], v179 offset:25664
	ds_read_b128 v[116:119], v179 offset:28224
	ds_read_b128 v[120:123], v178 offset:2624
	ds_read_b128 v[100:103], v178 offset:5184
	ds_read_b128 v[96:99], v178 offset:7744
	s_cmp_gt_u32 s1, 14
	s_cbranch_scc1 .LBB0_1420
	v_lshl_add_u64 v[72:73], v[168:169], 0, s[8:9]
	v_add_co_u32_e32 v64, vcc, 0x1d00000, v72
	v_lshl_add_u64 v[88:89], v[170:171], 0, s[8:9]
	s_nop 0
	v_addc_co_u32_e32 v65, vcc, 0, v73, vcc
	v_add_co_u32_e32 v68, vcc, 0x1d10000, v72
	s_nop 1
	v_addc_co_u32_e32 v69, vcc, 0, v73, vcc
	v_add_co_u32_e32 v74, vcc, 0x1d20000, v72
	global_load_dwordx4 v[64:67], v[64:65], off offset:128
	s_nop 0
	global_load_dwordx4 v[68:71], v[68:69], off offset:128
	v_addc_co_u32_e32 v75, vcc, 0, v73, vcc
	v_add_co_u32_e32 v72, vcc, 0x1d30000, v72
	s_nop 1
	v_addc_co_u32_e32 v73, vcc, 0, v73, vcc
	global_load_dwordx4 v[76:79], v[74:75], off offset:128
	global_load_dwordx4 v[84:87], v[72:73], off offset:128
	v_add_co_u32_e32 v72, vcc, 0x680000, v88
	s_nop 1
	v_addc_co_u32_e32 v73, vcc, 0, v89, vcc
	v_add_co_u32_e32 v80, vcc, 0x690000, v88
	s_nop 1
	v_addc_co_u32_e32 v81, vcc, 0, v89, vcc
	v_add_co_u32_e32 v90, vcc, 0x6a0000, v88
	global_load_dwordx4 v[72:75], v[72:73], off offset:128
	s_nop 0
	global_load_dwordx4 v[80:83], v[80:81], off offset:128
	v_addc_co_u32_e32 v91, vcc, 0, v89, vcc
	v_add_co_u32_e32 v92, vcc, 0x6b0000, v88
	s_nop 1
	v_addc_co_u32_e32 v93, vcc, 0, v89, vcc
	global_load_dwordx4 v[88:91], v[90:91], off offset:128
	s_nop 0
	global_load_dwordx4 v[92:95], v[92:93], off offset:128
	s_branch .LBB0_1420

; template <bool DEEP, class Epi>
; __device__ __forceinline__ void gemm_phase(const bf16_t* __restrict__ A, int lda, const bf16_t* __restrict__ Wt,
;                                            int K, int ntn, bool lat_only, const Epi& epi, char* smem) {
;     ...
;     for (int kt = 0; kt < nk; ++kt) {
;       __syncthreads();
;       GEMM_STORE(ra0, ra1, ra2, ra3, rb0, rb1, rb2, rb3, 0)
;       __syncthreads();
;       {
;         bf16x8 af0[4], bf0[4], af1[4], bf1[4];
;         __builtin_amdgcn_s_setprio(1);
; #pragma unroll
;         for (int i = 0; i < 4; ++i) af0[i] = *(const bf16x8*)(sA + (wm * 64 + i * 16 + l15) * LSTR + quad * 8);
; #pragma unroll
;         for (int j = 0; j < 4; ++j) bf0[j] = *(const bf16x8*)(sB + (wn * 64 + j * 16 + l15) * LSTR + quad * 8);
; #pragma unroll
;         for (int i = 0; i < 4; ++i) af1[i] = *(const bf16x8*)(sA + (wm * 64 + i * 16 + l15) * LSTR + 32 + quad * 8);
; #pragma unroll
;         for (int j = 0; j < 4; ++j) bf1[j] = *(const bf16x8*)(sB + (wn * 64 + j * 16 + l15) * LSTR + 32 + quad * 8);
;         __builtin_amdgcn_sched_barrier(0);
;         if (kt + 1 < nk) GEMM_LOAD(ra0, ra1, ra2, ra3, rb0, rb1, rb2, rb3, (kt + 1) * 64)
;         __builtin_amdgcn_sched_barrier(0);
; #pragma unroll
;         for (int i = 0; i < 4; ++i)
; #pragma unroll
;           for (int j = 0; j < 4; ++j) acc[i][j] = __builtin_amdgcn_mfma_f32_16x16x32_bf16(bf0[j], af0[i], acc[i][j], 0, 0, 0);
; #pragma unroll
;         for (int i = 0; i < 4; ++i)
; #pragma unroll
;           for (int j = 0; j < 4; ++j) acc[i][j] = __builtin_amdgcn_mfma_f32_16x16x32_bf16(bf1[j], af1[i], acc[i][j], 0, 0, 0);
;         __builtin_amdgcn_s_setprio(0);
.LBB0_1558:
	s_waitcnt lgkmcnt(14)
	v_mfma_f32_16x16x32_bf16 v[68:71], v[136:139], v[156:159], v[68:71]
	s_waitcnt lgkmcnt(13)
	v_mfma_f32_16x16x32_bf16 v[48:51], v[140:143], v[156:159], v[48:51]
	s_waitcnt lgkmcnt(12)
	v_mfma_f32_16x16x32_bf16 v[76:79], v[144:147], v[156:159], v[76:79]
	s_waitcnt lgkmcnt(11)
	v_mfma_f32_16x16x32_bf16 v[52:55], v[148:151], v[156:159], v[52:55]
	s_waitcnt lgkmcnt(10)
	v_mfma_f32_16x16x32_bf16 v[40:43], v[136:139], v[152:155], v[40:43]
	v_mfma_f32_16x16x32_bf16 v[32:35], v[140:143], v[152:155], v[32:35]
	v_mfma_f32_16x16x32_bf16 v[44:47], v[144:147], v[152:155], v[44:47]
	v_mfma_f32_16x16x32_bf16 v[36:39], v[148:151], v[152:155], v[36:39]
	s_waitcnt lgkmcnt(9)
	v_mfma_f32_16x16x32_bf16 v[24:27], v[136:139], v[132:135], v[24:27]
	v_mfma_f32_16x16x32_bf16 v[16:19], v[140:143], v[132:135], v[16:19]
	v_mfma_f32_16x16x32_bf16 v[28:31], v[144:147], v[132:135], v[28:31]
	v_mfma_f32_16x16x32_bf16 v[20:23], v[148:151], v[132:135], v[20:23]
	s_waitcnt lgkmcnt(8)
	v_mfma_f32_16x16x32_bf16 v[8:11], v[136:139], v[124:127], v[8:11]
	v_mfma_f32_16x16x32_bf16 v[0:3], v[140:143], v[124:127], v[0:3]
	v_mfma_f32_16x16x32_bf16 v[12:15], v[144:147], v[124:127], v[12:15]
	v_mfma_f32_16x16x32_bf16 v[4:7], v[148:151], v[124:127], v[4:7]
	s_waitcnt lgkmcnt(6)
	v_mfma_f32_16x16x32_bf16 v[68:71], v[104:107], v[128:131], v[68:71]
	s_waitcnt lgkmcnt(5)
	v_mfma_f32_16x16x32_bf16 v[48:51], v[108:111], v[128:131], v[48:51]
	s_waitcnt lgkmcnt(4)
	v_mfma_f32_16x16x32_bf16 v[76:79], v[112:115], v[128:131], v[76:79]
	s_waitcnt lgkmcnt(3)
	v_mfma_f32_16x16x32_bf16 v[52:55], v[116:119], v[128:131], v[52:55]
	s_waitcnt lgkmcnt(2)
	v_mfma_f32_16x16x32_bf16 v[40:43], v[104:107], v[120:123], v[40:43]
	v_mfma_f32_16x16x32_bf16 v[32:35], v[108:111], v[120:123], v[32:35]
	v_mfma_f32_16x16x32_bf16 v[44:47], v[112:115], v[120:123], v[44:47]
	v_mfma_f32_16x16x32_bf16 v[36:39], v[116:119], v[120:123], v[36:39]
	s_waitcnt lgkmcnt(1)
	v_mfma_f32_16x16x32_bf16 v[24:27], v[104:107], v[100:103], v[24:27]
	v_mfma_f32_16x16x32_bf16 v[16:19], v[108:111], v[100:103], v[16:19]
	v_mfma_f32_16x16x32_bf16 v[28:31], v[112:115], v[100:103], v[28:31]
	v_mfma_f32_16x16x32_bf16 v[20:23], v[116:119], v[100:103], v[20:23]
	s_waitcnt lgkmcnt(0)
	v_mfma_f32_16x16x32_bf16 v[8:11], v[104:107], v[96:99], v[8:11]
	v_mfma_f32_16x16x32_bf16 v[0:3], v[108:111], v[96:99], v[0:3]
	v_mfma_f32_16x16x32_bf16 v[12:15], v[112:115], v[96:99], v[12:15]
	v_mfma_f32_16x16x32_bf16 v[4:7], v[116:119], v[96:99], v[4:7]
	s_setprio 0
	s_add_u32 s6, s6, 0x80
	s_addc_u32 s7, s7, 0
	s_cmpk_eq_i32 s6, 0x800
	s_cbranch_scc1 .LBB0_1556
.LBB0_1559:
	s_barrier
	s_waitcnt vmcnt(7)
	ds_write_b128 v172, v[56:59]
	s_waitcnt vmcnt(6)
	ds_write_b128 v172, v[60:63] offset:5120
	s_waitcnt vmcnt(5)
	ds_write_b128 v172, v[64:67] offset:10240
	s_waitcnt vmcnt(4)
	ds_write_b128 v172, v[72:75] offset:15360
	s_waitcnt vmcnt(3)
	ds_write_b128 v172, v[80:83] offset:20480
	s_waitcnt vmcnt(2)
	ds_write_b128 v172, v[84:87] offset:25600
	s_waitcnt vmcnt(1)
	ds_write_b128 v172, v[88:91] offset:30720
	s_waitcnt vmcnt(0)
	ds_write_b128 v172, v[92:95] offset:35840
	s_waitcnt lgkmcnt(0)
	s_barrier
	s_setprio 1
	v_add_u32_e32 v96, v174, v175
	ds_read_b128 v[156:159], v96
	ds_read_b128 v[136:139], v176 offset:20480
	ds_read_b128 v[140:143], v176 offset:23040
	ds_read_b128 v[144:147], v176 offset:25600
	ds_read_b128 v[148:151], v176 offset:28160
	ds_read_b128 v[152:155], v96 offset:2560
	ds_read_b128 v[132:135], v96 offset:5120
	ds_read_b128 v[124:127], v96 offset:7680
	ds_read_b128 v[128:131], v177 offset:64
	ds_read_b128 v[104:107], v178 offset:20544
	ds_read_b128 v[108:111], v178 offset:23104
	ds_read_b128 v[112:115], v178 offset:25664
	ds_read_b128 v[116:119], v178 offset:28224
	ds_read_b128 v[120:123], v177 offset:2624
	ds_read_b128 v[100:103], v177 offset:5184
	ds_read_b128 v[96:99], v177 offset:7744
	s_cmpk_eq_i32 s6, 0x780
	s_cbranch_scc1 .LBB0_1558
	v_lshl_add_u64 v[64:65], v[168:169], 0, s[6:7]
	v_add_co_u32_e32 v56, vcc, 0x1d00000, v64
	v_lshl_add_u64 v[88:89], v[170:171], 0, s[6:7]
	s_nop 0
	v_addc_co_u32_e32 v57, vcc, 0, v65, vcc
	v_add_co_u32_e32 v60, vcc, 0x1d10000, v64
	s_nop 1
	v_addc_co_u32_e32 v61, vcc, 0, v65, vcc
	v_add_co_u32_e32 v66, vcc, 0x1d20000, v64
	global_load_dwordx4 v[56:59], v[56:57], off offset:128
	s_nop 0
	global_load_dwordx4 v[60:63], v[60:61], off offset:128
	v_addc_co_u32_e32 v67, vcc, 0, v65, vcc
	v_add_co_u32_e32 v72, vcc, 0x1d30000, v64
	s_nop 1
	v_addc_co_u32_e32 v73, vcc, 0, v65, vcc
	v_add_co_u32_e32 v80, vcc, 0x880000, v88
	global_load_dwordx4 v[64:67], v[66:67], off offset:128
	s_nop 0
	global_load_dwordx4 v[72:75], v[72:73], off offset:128
	v_addc_co_u32_e32 v81, vcc, 0, v89, vcc
	v_add_co_u32_e32 v84, vcc, 0x890000, v88
	s_nop 1
	v_addc_co_u32_e32 v85, vcc, 0, v89, vcc
	v_add_co_u32_e32 v90, vcc, 0x8a0000, v88
	global_load_dwordx4 v[80:83], v[80:81], off offset:128
	s_nop 0
	global_load_dwordx4 v[84:87], v[84:85], off offset:128
	v_addc_co_u32_e32 v91, vcc, 0, v89, vcc
	v_add_co_u32_e32 v92, vcc, 0x8b0000, v88
	s_nop 1
	v_addc_co_u32_e32 v93, vcc, 0, v89, vcc
	global_load_dwordx4 v[88:91], v[90:91], off offset:128
	s_nop 0
	global_load_dwordx4 v[92:95], v[92:93], off offset:128
	s_branch .LBB0_1558

; template <bool DEEP, class Epi>
; __device__ __forceinline__ void gemm_phase(const bf16_t* __restrict__ A, int lda, const bf16_t* __restrict__ Wt,
;                                            int K, int ntn, bool lat_only, const Epi& epi, char* smem) {
;     ...
;     for (int kt = 0; kt < nk; ++kt) {
;       __syncthreads();
;       GEMM_STORE(ra0, ra1, ra2, ra3, rb0, rb1, rb2, rb3, 0)
;       __syncthreads();
;       {
;         bf16x8 af0[4], bf0[4], af1[4], bf1[4];
;         __builtin_amdgcn_s_setprio(1);
; #pragma unroll
;         for (int i = 0; i < 4; ++i) af0[i] = *(const bf16x8*)(sA + (wm * 64 + i * 16 + l15) * LSTR + quad * 8);
; #pragma unroll
;         for (int j = 0; j < 4; ++j) bf0[j] = *(const bf16x8*)(sB + (wn * 64 + j * 16 + l15) * LSTR + quad * 8);
; #pragma unroll
;         for (int i = 0; i < 4; ++i) af1[i] = *(const bf16x8*)(sA + (wm * 64 + i * 16 + l15) * LSTR + 32 + quad * 8);
; #pragma unroll
;         for (int j = 0; j < 4; ++j) bf1[j] = *(const bf16x8*)(sB + (wn * 64 + j * 16 + l15) * LSTR + 32 + quad * 8);
;         __builtin_amdgcn_sched_barrier(0);
;         if (kt + 1 < nk) GEMM_LOAD(ra0, ra1, ra2, ra3, rb0, rb1, rb2, rb3, (kt + 1) * 64)
;         __builtin_amdgcn_sched_barrier(0);
; #pragma unroll
;         for (int i = 0; i < 4; ++i)
; #pragma unroll
;           for (int j = 0; j < 4; ++j) acc[i][j] = __builtin_amdgcn_mfma_f32_16x16x32_bf16(bf0[j], af0[i], acc[i][j], 0, 0, 0);
; #pragma unroll
;         for (int i = 0; i < 4; ++i)
; #pragma unroll
;           for (int j = 0; j < 4; ++j) acc[i][j] = __builtin_amdgcn_mfma_f32_16x16x32_bf16(bf1[j], af1[i], acc[i][j], 0, 0, 0);
;         __builtin_amdgcn_s_setprio(0);
.LBB0_1618:
	s_barrier
	s_waitcnt vmcnt(0)
	ds_write_b128 v168, v[64:67]
	ds_write_b128 v168, v[72:75] offset:5120
	ds_write_b128 v168, v[80:83] offset:10240
	ds_write_b128 v168, v[88:91] offset:15360
	ds_write_b128 v168, v[68:71] offset:20480
	ds_write_b128 v168, v[76:79] offset:25600
	ds_write_b128 v168, v[84:87] offset:30720
	ds_write_b128 v168, v[92:95] offset:35840
	s_waitcnt lgkmcnt(0)
	s_barrier
	s_setprio 1
	v_add_u32_e32 v96, v170, v172
	ds_read_b128 v[156:159], v96
	ds_read_b128 v[136:139], v174 offset:20480
	ds_read_b128 v[140:143], v174 offset:23040
	ds_read_b128 v[144:147], v174 offset:25600
	ds_read_b128 v[148:151], v174 offset:28160
	ds_read_b128 v[152:155], v96 offset:2560
	ds_read_b128 v[132:135], v96 offset:5120
	ds_read_b128 v[124:127], v96 offset:7680
	ds_read_b128 v[128:131], v175 offset:64
	ds_read_b128 v[104:107], v176 offset:20544
	ds_read_b128 v[108:111], v176 offset:23104
	ds_read_b128 v[112:115], v176 offset:25664
	ds_read_b128 v[116:119], v176 offset:28224
	ds_read_b128 v[120:123], v175 offset:2624
	ds_read_b128 v[100:103], v175 offset:5184
	ds_read_b128 v[96:99], v175 offset:7744
	s_cmp_gt_u32 s15, 42
	s_cbranch_scc1 .LBB0_1617
	v_lshl_add_u64 v[68:69], v[164:165], 0, s[0:1]
	v_add_co_u32_e32 v64, vcc, 0x5e00000, v68
	v_lshl_add_u64 v[84:85], v[166:167], 0, s[0:1]
	s_nop 0
	v_addc_co_u32_e32 v65, vcc, 0, v69, vcc
	v_add_co_u32_e32 v70, vcc, 0x5e2c000, v68
	s_nop 1
	v_addc_co_u32_e32 v71, vcc, 0, v69, vcc
	global_load_dwordx4 v[64:67], v[64:65], off offset:128
	s_nop 0
	global_load_dwordx4 v[72:75], v[70:71], off offset:128
	v_add_co_u32_e32 v70, vcc, 0x5e58000, v68
	s_nop 1
	v_addc_co_u32_e32 v71, vcc, 0, v69, vcc
	v_add_co_u32_e32 v68, vcc, 0x5e84000, v68
	s_nop 1
	v_addc_co_u32_e32 v69, vcc, 0, v69, vcc
	global_load_dwordx4 v[80:83], v[70:71], off offset:128
	global_load_dwordx4 v[88:91], v[68:69], off offset:128
	v_add_co_u32_e32 v68, vcc, 0x1380000, v84
	s_nop 1
	v_addc_co_u32_e32 v69, vcc, 0, v85, vcc
	v_add_co_u32_e32 v76, vcc, 0x13ac000, v84
	s_nop 1
	v_addc_co_u32_e32 v77, vcc, 0, v85, vcc
	v_add_co_u32_e32 v86, vcc, 0x13d8000, v84
	global_load_dwordx4 v[68:71], v[68:69], off offset:128
	s_nop 0
	global_load_dwordx4 v[76:79], v[76:77], off offset:128
	v_addc_co_u32_e32 v87, vcc, 0, v85, vcc
	v_add_co_u32_e32 v92, vcc, 0x1404000, v84
	s_nop 1
	v_addc_co_u32_e32 v93, vcc, 0, v85, vcc
	global_load_dwordx4 v[84:87], v[86:87], off offset:128
	s_nop 0
	global_load_dwordx4 v[92:95], v[92:93], off offset:128
	s_branch .LBB0_1617
